# retention loop restructured: V(t+1) DMA needed only at barrier 1 of next tile, K(t+2) DMA issued after barrier 1, counted vmcnt(8) keeps 8 DMA in flight
# speedup vs baseline: 1.0110x; 1.0110x over previous
.LBB0_802:
	s_or_b64 exec, exec, s[0:1]
	s_mov_b32 s0, 0xbfb8aa3b
	s_waitcnt vmcnt(0)
	v_mul_f32_e64 v195, |v0|, s0
	v_mul_f32_e64 v201, |v1|, s0
	s_or_b32 s0, s7, s4
	s_mul_hi_u32 s1, s0, 0x3000
	s_mulk_i32 s20, 0x3000
	s_add_i32 s1, s1, s20
	s_mulk_i32 s0, 0x3000
	v_readlane_b32 s8, v254, 39
	v_readlane_b32 s9, v254, 40
	s_add_u32 s0, s8, s0
	s_addc_u32 s1, s9, s1
	s_add_u32 s0, s0, s5
	s_mul_hi_u32 s21, s7, 0x3000
	s_addc_u32 s1, s1, 0
	s_add_i32 s21, s21, s20
	s_mulk_i32 s7, 0x3000
	s_add_u32 s7, s8, s7
	s_addc_u32 s21, s9, s21
	s_add_u32 s20, s7, s5
	s_addc_u32 s21, s21, 0
	s_ashr_i32 s7, s6, 31
	s_lshl_b64 s[6:7], s[6:7], 11
	s_or_b32 s5, s6, s5
	v_mov_b32_e32 v4, v192
	s_or_b32 s5, s5, s26
	s_mul_i32 s6, s7, 0x2400
	v_and_b32_e32 v189, 31, v4
	s_mul_hi_u32 s7, s5, 0x2400
	v_mul_u32_u24_e32 v0, 0x1800, v189
	s_add_i32 s7, s7, s6
	s_mulk_i32 s5, 0x2400
	v_readlane_b32 s8, v254, 41
	v_bfe_u32 v5, v4, 5, 1
	v_lshlrev_b32_e32 v0, 1, v0
	v_mov_b32_e32 v1, v112
	v_ashrrev_i32_e32 v193, 6, v4
	v_readlane_b32 s9, v254, 42
	s_add_u32 s6, s8, s5
	v_lshl_add_u64 v[0:1], s[0:1], 0, v[0:1]
	v_lshlrev_b32_e32 v2, 4, v5
	v_mov_b32_e32 v3, v112
	v_readfirstlane_b32 s0, v193
	s_addc_u32 s7, s9, s7
	v_lshl_add_u64 v[0:1], v[0:1], 0, v[2:3]
	s_lshl_b32 s5, s0, 3
	global_load_dwordx4 v[142:145], v[0:1], off
	global_load_dwordx4 v[138:141], v[0:1], off offset:32
	global_load_dwordx4 v[134:137], v[0:1], off offset:64
	global_load_dwordx4 v[130:133], v[0:1], off offset:96
	global_load_dwordx4 v[126:129], v[0:1], off offset:128
	global_load_dwordx4 v[122:125], v[0:1], off offset:160
	global_load_dwordx4 v[118:121], v[0:1], off offset:192
	global_load_dwordx4 v[114:117], v[0:1], off offset:224
	global_load_dwordx4 v[108:111], v[0:1], off offset:256
	global_load_dwordx4 v[104:107], v[0:1], off offset:288
	global_load_dwordx4 v[100:103], v[0:1], off offset:320
	global_load_dwordx4 v[96:99], v[0:1], off offset:352
	global_load_dwordx4 v[92:95], v[0:1], off offset:384
	global_load_dwordx4 v[88:91], v[0:1], off offset:416
	global_load_dwordx4 v[84:87], v[0:1], off offset:448
	global_load_dwordx4 v[80:83], v[0:1], off offset:480
	v_or_b32_e32 v1, s5, v5
	v_bitop3_b32 v2, s5, v4, v5 bitop3:0x36
	s_movk_i32 s28, 0x1800
	v_mul_lo_u32 v1, v1, s28
	v_lshlrev_b32_e32 v2, 3, v2
	s_movk_i32 s27, 0xf8
	v_bfe_u32 v0, v4, 3, 3
	v_and_or_b32 v1, v2, s27, v1
	v_bfe_u32 v2, v4, 4, 2
	s_lshl_b32 s1, s0, 2
	v_lshlrev_b32_e32 v146, 1, v1
	v_lshl_or_b32 v1, s0, 5, v0
	v_xor_b32_e32 v2, v2, v4
	s_movk_i32 s29, 0x1200
	v_mul_lo_u32 v1, v1, s29
	v_lshlrev_b32_e32 v2, 3, v2
	s_or_b32 s5, s1, 1
	v_and_or_b32 v1, v2, 56, v1
	s_lshl_b32 s26, s5, 1
	v_lshlrev_b32_e32 v148, 1, v1
	v_or_b32_e32 v1, s26, v5
	v_bitop3_b32 v2, s26, v4, v5 bitop3:0x36
	v_mul_lo_u32 v1, v1, s28
	v_lshlrev_b32_e32 v2, 3, v2
	v_and_or_b32 v1, v2, s27, v1
	v_lshlrev_b32_e32 v150, 1, v1
	v_lshl_or_b32 v1, s5, 3, v0
	v_lshrrev_b32_e32 v2, 1, v1
	v_xor_b32_e32 v2, v2, v4
	v_mul_lo_u32 v1, v1, s29
	v_lshlrev_b32_e32 v2, 3, v2
	s_or_b32 s5, s1, 2
	v_and_or_b32 v1, v2, 56, v1
	s_lshl_b32 s26, s5, 1
	v_lshlrev_b32_e32 v152, 1, v1
	v_or_b32_e32 v1, s26, v5
	v_bitop3_b32 v2, s26, v4, v5 bitop3:0x36
	v_mul_lo_u32 v1, v1, s28
	v_lshlrev_b32_e32 v2, 3, v2
	v_and_or_b32 v1, v2, s27, v1
	v_lshlrev_b32_e32 v154, 1, v1
	v_lshl_or_b32 v1, s5, 3, v0
	v_lshrrev_b32_e32 v2, 1, v1
	v_xor_b32_e32 v2, v2, v4
	v_mul_lo_u32 v1, v1, s29
	v_lshlrev_b32_e32 v2, 3, v2
	s_or_b32 s1, s1, 3
	v_and_or_b32 v1, v2, 56, v1
	s_lshl_b32 s5, s1, 1
	v_lshlrev_b32_e32 v156, 1, v1
	v_or_b32_e32 v1, s5, v5
	v_bitop3_b32 v2, s5, v4, v5 bitop3:0x36
	v_mul_lo_u32 v1, v1, s28
	v_lshlrev_b32_e32 v2, 3, v2
	v_and_or_b32 v1, v2, s27, v1
	v_lshl_or_b32 v0, s1, 3, v0
	v_lshlrev_b32_e32 v158, 1, v1
	v_lshrrev_b32_e32 v1, 1, v0
	v_xor_b32_e32 v1, v1, v4
	v_mul_lo_u32 v0, v0, s29
	v_lshlrev_b32_e32 v1, 3, v1
	v_and_or_b32 v0, v1, 56, v0
	v_lshlrev_b32_e32 v160, 1, v0
	v_mul_f32_e32 v0, 0xc1000000, v195
	v_exp_f32_e64 v2, -v195
	v_exp_f32_e32 v0, v0
	v_exp_f32_e32 v1, v201
	v_mov_b32_e32 v147, v112
	v_readfirstlane_b32 s30, v2
	v_readfirstlane_b32 s31, v0
	v_mul_f32_e32 v0, 0x41000000, v201
	v_mul_f32_e64 v170, s30, s30
	v_readfirstlane_b32 s34, v1
	v_exp_f32_e32 v0, v0
	v_readfirstlane_b32 s1, v170
	v_mul_f32_e64 v172, s34, s34
	s_mov_b64 s[26:27], 0x800
	v_mov_b32_e32 v2, s1
	v_readfirstlane_b32 s1, v172
	v_readfirstlane_b32 s35, v0
	v_mov_b32_e32 v151, v112
	v_mov_b32_e32 v1, s1
	s_lshl_b32 s1, s0, 12
	v_mul_f32_e32 v173, s34, v1
	v_lshl_add_u64 v[0:1], s[20:21], 0, v[146:147]
	s_add_i32 s36, s1, 0
	v_lshl_add_u64 v[0:1], v[0:1], 0, s[26:27]
	s_mov_b32 m0, s36
	v_mov_b32_e32 v155, v112
	global_load_lds_dwordx4 v[0:1], off
	v_lshl_add_u64 v[0:1], s[20:21], 0, v[150:151]
	v_lshl_add_u64 v[0:1], v[0:1], 0, s[26:27]
	s_add_i32 m0, s36, 0x400
	v_mov_b32_e32 v159, v112
	global_load_lds_dwordx4 v[0:1], off
	v_lshl_add_u64 v[0:1], s[20:21], 0, v[154:155]
	v_lshl_add_u64 v[0:1], v[0:1], 0, s[26:27]
	s_add_i32 m0, s36, 0x800
	v_or_b32_e32 v162, s4, v189
	global_load_lds_dwordx4 v[0:1], off
	v_lshl_add_u64 v[0:1], s[20:21], 0, v[158:159]
	v_lshl_add_u64 v[0:1], v[0:1], 0, s[26:27]
	s_add_i32 m0, s36, 0xc00
	s_lshl_b32 s0, s0, 11
	global_load_lds_dwordx4 v[0:1], off
	s_add_i32 m0, s36, 0x8000
	v_bitop3_b32 v0, v5, v4, 31 bitop3:0x78
	global_load_lds_dwordx4 v148, s[6:7]
	s_add_i32 m0, s36, 0x8400
	v_lshlrev_b32_e32 v216, 4, v0
	global_load_lds_dwordx4 v152, s[6:7]
	s_add_i32 m0, s36, 0x8800
	v_lshrrev_b32_e32 v0, 1, v4
	global_load_lds_dwordx4 v156, s[6:7]
	s_add_i32 m0, s36, 0x8c00
	v_bitop3_b32 v0, v0, v5, 7 bitop3:0x6c
	global_load_lds_dwordx4 v160, s[6:7]
	v_lshlrev_b32_e32 v213, 4, v0
	v_sub_u32_e32 v0, 0x1000, v162
	v_cvt_f32_u32_e32 v0, v0
	v_add_u32_e32 v1, 1, v162
	v_cvt_f32_u32_e32 v1, v1
	s_add_i32 s56, 0, 0x20000
	s_add_i32 s37, s56, s0
	s_xor_b32 s0, s0, 0x2000
	s_add_i32 s24, s24, s25
	s_lshl_b32 s20, s22, 3
	v_lshlrev_b32_e32 v190, 2, v5
	s_add_i32 s56, s56, s0
	s_lshl_b32 s0, s64, 14
	s_lshl_b32 s28, s64, 6
	v_mul_f32_e32 v214, v201, v0
	v_add_u32_e32 v0, s24, v189
	s_mul_i32 s1, s23, 0x3000
	s_and_b32 s20, s20, 0x600
	s_waitcnt vmcnt(0)
	s_lshl_b32 s57, s64, 5
	s_or_b32 s27, s28, 32
	v_mul_f32_e32 v218, v195, v1
	s_or_b32 s55, s4, 31
	s_sub_i32 s26, 64, s28
	s_sub_i32 s5, 0x60, s28
	s_add_i32 s29, s0, 0
	v_sub_u32_e32 v1, v0, v190
	s_or_b32 s1, s1, s20
	v_and_b32_e32 v191, 63, v4
	v_or_b32_e32 v219, s57, v190
	v_subrev_u32_e32 v220, s57, v1
	s_mul_hi_i32 s0, s23, 0x3000
	s_add_u32 s20, s84, s1
	v_mov_b32_e32 v48, 0
	v_mul_f32_e32 v171, s30, v2
	v_mov_b32_e32 v149, v112
	v_mov_b32_e32 v153, v112
	v_mov_b32_e32 v157, v112
	v_mov_b32_e32 v161, v112
	v_lshlrev_b32_e32 v215, 9, v189
	v_lshlrev_b32_e32 v217, 4, v191
	v_lshlrev_b32_e32 v202, 7, v189
	v_mov_b32_e32 v113, v162
	v_subrev_u32_e32 v221, 27, v220
	v_subrev_u32_e32 v222, 26, v220
	v_sub_u32_e32 v223, v219, v0
	s_addc_u32 s21, s42, s0
	s_mov_b32 s63, 0
	s_mov_b64 s[22:23], 0x80
	s_mov_b32 s58, 0
	s_mov_b32 s59, 0
	s_mov_b32 s62, 0
	v_mov_b32_e32 v49, v48
	v_mov_b32_e32 v50, v48
	v_mov_b32_e32 v51, v48
	v_mov_b32_e32 v52, v48
	v_mov_b32_e32 v53, v48
	v_mov_b32_e32 v54, v48
	v_mov_b32_e32 v55, v48
	v_mov_b32_e32 v56, v48
	v_mov_b32_e32 v57, v48
	v_mov_b32_e32 v58, v48
	v_mov_b32_e32 v59, v48
	v_mov_b32_e32 v60, v48
	v_mov_b32_e32 v61, v48
	v_mov_b32_e32 v62, v48
	v_mov_b32_e32 v63, v48
	v_mov_b32_e32 v32, v48
	v_mov_b32_e32 v33, v48
	v_mov_b32_e32 v34, v48
	v_mov_b32_e32 v35, v48
	v_mov_b32_e32 v36, v48
	v_mov_b32_e32 v37, v48
	v_mov_b32_e32 v38, v48
	v_mov_b32_e32 v39, v48
	v_mov_b32_e32 v40, v48
	v_mov_b32_e32 v41, v48
	v_mov_b32_e32 v42, v48
	v_mov_b32_e32 v43, v48
	v_mov_b32_e32 v44, v48
	v_mov_b32_e32 v45, v48
	v_mov_b32_e32 v46, v48
	v_mov_b32_e32 v47, v48
	v_mov_b32_e32 v16, v48
	v_mov_b32_e32 v17, v48
	v_mov_b32_e32 v18, v48
	v_mov_b32_e32 v19, v48
	v_mov_b32_e32 v20, v48
	v_mov_b32_e32 v21, v48
	v_mov_b32_e32 v22, v48
	v_mov_b32_e32 v23, v48
	v_mov_b32_e32 v24, v48
	v_mov_b32_e32 v25, v48
	v_mov_b32_e32 v26, v48
	v_mov_b32_e32 v27, v48
	v_mov_b32_e32 v28, v48
	v_mov_b32_e32 v29, v48
	v_mov_b32_e32 v30, v48
	v_mov_b32_e32 v31, v48
	v_mov_b32_e32 v0, v48
	v_mov_b32_e32 v1, v48
	v_mov_b32_e32 v2, v48
	v_mov_b32_e32 v3, v48
	v_mov_b32_e32 v4, v48
	v_mov_b32_e32 v5, v48
	v_mov_b32_e32 v6, v48
	v_mov_b32_e32 v7, v48
	v_mov_b32_e32 v8, v48
	v_mov_b32_e32 v9, v48
	v_mov_b32_e32 v10, v48
	v_mov_b32_e32 v11, v48
	v_mov_b32_e32 v12, v48
	v_mov_b32_e32 v13, v48
	v_mov_b32_e32 v14, v48
	v_mov_b32_e32 v15, v48
	s_add_i32 s0, s36, 0x10000
	v_lshl_add_u64 v[64:65], s[20:21], 0, v[146:147]
	s_mov_b32 m0, s0
	s_nop 0
	global_load_lds_dwordx4 v[64:65], off
	v_lshl_add_u64 v[64:65], s[20:21], 0, v[150:151]
	s_add_i32 m0, s0, 0x400
	s_nop 0
	global_load_lds_dwordx4 v[64:65], off
	v_lshl_add_u64 v[64:65], s[20:21], 0, v[154:155]
	s_add_i32 m0, s0, 0x800
	s_nop 0
	global_load_lds_dwordx4 v[64:65], off
	v_lshl_add_u64 v[64:65], s[20:21], 0, v[158:159]
	s_add_i32 m0, s0, 0xc00
	s_nop 0
	global_load_lds_dwordx4 v[64:65], off
	s_waitcnt vmcnt(4) lgkmcnt(0)
	s_barrier
	s_branch .LBB0_804
.LBB0_803:
	s_nop 6
	v_mul_f32_e32 v71, v79, v188
	v_cvt_pk_bf16_f32 v64, v174, v175
	v_cvt_pk_bf16_f32 v65, v176, v177
	v_cvt_pk_bf16_f32 v66, v178, v179
	v_cvt_pk_bf16_f32 v67, v180, v181
	v_add_u32_e32 v175, s37, v217
	v_cvt_pk_bf16_f32 v68, v182, v183
	v_cvt_pk_bf16_f32 v69, v184, v185
	v_cvt_pk_bf16_f32 v70, v186, v187
	v_cvt_pk_bf16_f32 v71, v194, v71
	ds_write_b128 v175, v[64:67]
	ds_write_b128 v175, v[68:71] offset:1024
	v_add_u32_e32 v224, s0, v202
	v_add_u32_e32 v224, v224, v213
	v_add_u32_e32 v224, 0x8000, v224
	v_add_u32_e32 v174, s56, v217
	s_add_i32 s59, s59, 64
	s_sub_i32 s58, s58, 64
	s_add_u32 s22, s22, 0x80
	s_addc_u32 s23, s23, 0
	s_add_u32 s20, s20, 0xc0000
	s_addc_u32 s21, s21, 0
	s_mov_b32 s63, s61
	s_mov_b32 s62, s60
	s_waitcnt vmcnt(8) lgkmcnt(0)
	s_barrier
	v_xor_b32_e32 v225, s28, v224
	ds_read_b128 v[228:231], v225
	ds_read_b128 v[232:235], v225 offset:4096
	ds_read_b128 v[236:239], v225 offset:8192
	ds_read_b128 v[240:243], v225 offset:12288
	v_xor_b32_e32 v225, s27, v224
	ds_read_b128 v[244:247], v225
	ds_read_b128 v[248:251], v225 offset:4096
	ds_read_b128 v[72:75], v225 offset:8192
	ds_read_b128 v[76:79], v225 offset:12288
	ds_read_b128 v[176:179], v174
	ds_read_b128 v[180:183], v174 offset:1024
	s_cmpk_gt_u32 s62, 70
	s_cbranch_scc1 .Lret_k_skip
	s_cmpk_lt_u32 s62, 63
	s_cbranch_scc0 .Lret_k_virt
	s_mov_b64 s[24:25], s[20:21]
	s_branch .Lret_k_issue
.Lret_k_virt:
	s_add_i32 s0, s62, 1
	s_and_b32 s0, s0, 3
	s_mul_i32 s0, s0, 0xc0000
	s_add_u32 s24, s40, s0
	s_addc_u32 s25, s41, 0
.Lret_k_issue:
	s_add_i32 s1, s63, 0x10000
	s_and_b32 s1, s1, 0x10000
	s_add_i32 s1, s36, s1
	v_lshl_add_u64 v[226:227], s[24:25], 0, v[146:147]
	s_mov_b32 m0, s1
	s_nop 0
	global_load_lds_dwordx4 v[226:227], off
	v_lshl_add_u64 v[226:227], s[24:25], 0, v[150:151]
	s_add_i32 m0, s1, 0x400
	s_nop 0
	global_load_lds_dwordx4 v[226:227], off
	v_lshl_add_u64 v[226:227], s[24:25], 0, v[154:155]
	s_add_i32 m0, s1, 0x800
	s_nop 0
	global_load_lds_dwordx4 v[226:227], off
	v_lshl_add_u64 v[226:227], s[24:25], 0, v[158:159]
	s_add_i32 m0, s1, 0xc00
	s_nop 0
	global_load_lds_dwordx4 v[226:227], off
.Lret_k_skip:
	s_waitcnt lgkmcnt(6)
	v_mfma_f32_32x32x16_bf16 v[48:63], v[228:231], v[64:67], v[48:63]
	v_mfma_f32_32x32x16_bf16 v[32:47], v[232:235], v[64:67], v[32:47]
	v_mfma_f32_32x32x16_bf16 v[16:31], v[236:239], v[64:67], v[16:31]
	v_mfma_f32_32x32x16_bf16 v[0:15], v[240:243], v[64:67], v[0:15]
	v_xor_b32_e32 v225, s26, v224
	ds_read_b128 v[228:231], v225
	ds_read_b128 v[232:235], v225 offset:4096
	ds_read_b128 v[236:239], v225 offset:8192
	ds_read_b128 v[240:243], v225 offset:12288
	s_waitcnt lgkmcnt(6)
	v_mfma_f32_32x32x16_bf16 v[48:63], v[244:247], v[68:71], v[48:63]
	v_mfma_f32_32x32x16_bf16 v[32:47], v[248:251], v[68:71], v[32:47]
	v_mfma_f32_32x32x16_bf16 v[16:31], v[72:75], v[68:71], v[16:31]
	v_mfma_f32_32x32x16_bf16 v[0:15], v[76:79], v[68:71], v[0:15]
	v_xor_b32_e32 v225, s5, v224
	ds_read_b128 v[244:247], v225
	ds_read_b128 v[248:251], v225 offset:4096
	ds_read_b128 v[72:75], v225 offset:8192
	ds_read_b128 v[76:79], v225 offset:12288
	s_waitcnt lgkmcnt(4)
	v_mfma_f32_32x32x16_bf16 v[48:63], v[228:231], v[176:179], v[48:63]
	v_mfma_f32_32x32x16_bf16 v[32:47], v[232:235], v[176:179], v[32:47]
	v_mfma_f32_32x32x16_bf16 v[16:31], v[236:239], v[176:179], v[16:31]
	v_mfma_f32_32x32x16_bf16 v[0:15], v[240:243], v[176:179], v[0:15]
	s_cmpk_eq_i32 s59, 0x11c0
	s_cbranch_scc1 .Lret_last_tile
	s_waitcnt vmcnt(8) lgkmcnt(0)
	s_barrier
	v_mfma_f32_32x32x16_bf16 v[48:63], v[244:247], v[180:183], v[48:63]
	v_mfma_f32_32x32x16_bf16 v[32:47], v[248:251], v[180:183], v[32:47]
	v_mfma_f32_32x32x16_bf16 v[16:31], v[72:75], v[180:183], v[16:31]
	v_mfma_f32_32x32x16_bf16 v[0:15], v[76:79], v[180:183], v[0:15]
	s_branch .LBB0_804
.Lret_last_tile:
	s_waitcnt vmcnt(0) lgkmcnt(0)
	s_barrier
	v_mfma_f32_32x32x16_bf16 v[48:63], v[244:247], v[180:183], v[48:63]
	v_mfma_f32_32x32x16_bf16 v[32:47], v[248:251], v[180:183], v[32:47]
	v_mfma_f32_32x32x16_bf16 v[16:31], v[72:75], v[180:183], v[16:31]
	v_mfma_f32_32x32x16_bf16 v[0:15], v[76:79], v[180:183], v[0:15]
	s_branch .LBB0_817
.LBB0_804:
	s_add_i32 s60, s62, 1
	s_lshl_b32 s0, s60, 7
	s_add_u32 s0, s6, s0
	s_addc_u32 s1, s7, 0
	s_add_i32 s61, s63, 0x10000
	s_and_b32 s64, s61, 0x10000
	s_add_i32 s64, s36, s64
	v_lshl_add_u64 v[64:65], s[0:1], 0, v[148:149]
	s_add_i32 m0, s64, 0x8000
	s_nop 0
	global_load_lds_dwordx4 v[64:65], off
	v_lshl_add_u64 v[64:65], s[0:1], 0, v[152:153]
	s_add_i32 m0, s64, 0x8400
	s_nop 0
	global_load_lds_dwordx4 v[64:65], off
	v_lshl_add_u64 v[64:65], s[0:1], 0, v[156:157]
	s_add_i32 m0, s64, 0x8800
	s_nop 0
	global_load_lds_dwordx4 v[64:65], off
	v_lshl_add_u64 v[64:65], s[0:1], 0, v[160:161]
	s_add_i32 m0, s64, 0x8c00
	s_nop 0
	global_load_lds_dwordx4 v[64:65], off
	s_and_b32 s0, s63, 0x10000
	s_add_i32 s0, s29, s0
	v_add3_u32 v164, s0, v215, v216
	v_xor_b32_e32 v68, 32, v164
	ds_read_b128 v[174:177], v68
	v_xor_b32_e32 v68, 64, v164
	ds_read_b128 v[178:181], v68
	v_xor_b32_e32 v68, 0x60, v164
	ds_read_b128 v[64:67], v164
	ds_read_b128 v[182:185], v68
	s_waitcnt lgkmcnt(0)
	v_mfma_f32_32x32x16_bf16 v[64:79], v[64:67], v[142:145], 0
	v_mfma_f32_32x32x16_bf16 v[64:79], v[174:177], v[138:141], v[64:79]
	v_xor_b32_e32 v165, 0x80, v164
	ds_read_b128 v[174:177], v165
	v_xor_b32_e32 v165, 0xa0, v164
	ds_read_b128 v[224:227], v165
	v_mfma_f32_32x32x16_bf16 v[64:79], v[178:181], v[134:137], v[64:79]
	v_mfma_f32_32x32x16_bf16 v[64:79], v[182:185], v[130:133], v[64:79]
	v_xor_b32_e32 v165, 0xc0, v164
	ds_read_b128 v[178:181], v165
	v_xor_b32_e32 v165, 0xe0, v164
	ds_read_b128 v[182:185], v165
	s_waitcnt lgkmcnt(0)
	v_mfma_f32_32x32x16_bf16 v[64:79], v[174:177], v[126:129], v[64:79]
	v_mfma_f32_32x32x16_bf16 v[64:79], v[224:227], v[122:125], v[64:79]
	v_xor_b32_e32 v165, 0x100, v164
	ds_read_b128 v[174:177], v165
	v_xor_b32_e32 v165, 0x120, v164
	ds_read_b128 v[224:227], v165
	v_mfma_f32_32x32x16_bf16 v[64:79], v[178:181], v[118:121], v[64:79]
	v_mfma_f32_32x32x16_bf16 v[64:79], v[182:185], v[114:117], v[64:79]
	v_xor_b32_e32 v165, 0x140, v164
	ds_read_b128 v[178:181], v165
	v_xor_b32_e32 v165, 0x160, v164
	ds_read_b128 v[182:185], v165
	s_waitcnt lgkmcnt(0)
	v_mfma_f32_32x32x16_bf16 v[64:79], v[174:177], v[108:111], v[64:79]
	v_mfma_f32_32x32x16_bf16 v[64:79], v[224:227], v[104:107], v[64:79]
	v_xor_b32_e32 v165, 0x180, v164
	ds_read_b128 v[174:177], v165
	v_xor_b32_e32 v165, 0x1a0, v164
	ds_read_b128 v[224:227], v165
	v_mfma_f32_32x32x16_bf16 v[64:79], v[178:181], v[100:103], v[64:79]
	v_mfma_f32_32x32x16_bf16 v[64:79], v[182:185], v[96:99], v[64:79]
	v_xor_b32_e32 v165, 0x1c0, v164
	v_xor_b32_e32 v164, 0x1e0, v164
	ds_read_b128 v[178:181], v165
	ds_read_b128 v[182:185], v164
	s_waitcnt lgkmcnt(0)
	v_mfma_f32_32x32x16_bf16 v[64:79], v[174:177], v[92:95], v[64:79]
	v_mfma_f32_32x32x16_bf16 v[64:79], v[224:227], v[88:91], v[64:79]
	v_mfma_f32_32x32x16_bf16 v[64:79], v[178:181], v[84:87], v[64:79]
	v_mfma_f32_32x32x16_bf16 v[64:79], v[182:185], v[80:83], v[64:79]
	s_cmpk_gt_u32 s59, 0xfff
	s_mov_b64 s[24:25], -1
	s_cbranch_scc0 .LBB0_808
	s_and_b32 s1, s62, 0x1fffffc
	s_cmp_eq_u32 s1, 64
	s_cselect_b64 vcc, -1, 0
	v_cndmask_b32_e32 v164, v214, v218, vcc
	v_exp_f32_e32 v188, v164
	s_mov_b64 s[24:25], 0
	s_nop 2
	v_pk_mul_f32 v[174:175], v[188:189], v[64:65] op_sel_hi:[0,1]
	v_pk_mul_f32 v[176:177], v[188:189], v[66:67] op_sel_hi:[0,1]
	v_pk_mul_f32 v[178:179], v[188:189], v[68:69] op_sel_hi:[0,1]
	v_pk_mul_f32 v[180:181], v[188:189], v[70:71] op_sel_hi:[0,1]
	v_pk_mul_f32 v[182:183], v[188:189], v[72:73] op_sel_hi:[0,1]
	v_pk_mul_f32 v[184:185], v[188:189], v[74:75] op_sel_hi:[0,1]
	v_pk_mul_f32 v[186:187], v[188:189], v[76:77] op_sel_hi:[0,1]
	v_mul_f32_e32 v194, v188, v78
